# SwiGLU epilogue re-associated with packed f32 ops (no s_nop chains); attention QK/PV straight-line fast paths with LDS reads issued ahead
# speedup vs baseline: 1.0102x; 1.0024x over previous
.Lqk_fast:
	s_mov_b64 s[6:7], -1
	s_mov_b64 s[10:11], -1
	s_mov_b64 s[12:13], -1
	s_mov_b64 s[14:15], -1
	s_mov_b64 s[36:37], s[74:75]
	ds_read_b128 v[82:85], v221
	ds_read_b128 v[86:89], v222
	ds_read_b128 v[90:93], v223
	ds_read_b128 v[94:97], v224
	ds_read_b128 v[98:101], v221 offset:4096
	ds_read_b128 v[102:105], v222 offset:4096
	ds_read_b128 v[106:109], v223 offset:4096
	ds_read_b128 v[110:113], v224 offset:4096
	s_waitcnt vmcnt(3) lgkmcnt(7)
	v_mfma_f32_32x32x16_bf16 v[50:65], v[82:85], v[130:133], 0
	s_waitcnt vmcnt(2) lgkmcnt(6)
	v_mfma_f32_32x32x16_bf16 v[50:65], v[86:89], v[134:137], v[50:65]
	s_waitcnt vmcnt(1) lgkmcnt(5)
	v_mfma_f32_32x32x16_bf16 v[50:65], v[90:93], v[138:141], v[50:65]
	s_waitcnt vmcnt(0) lgkmcnt(4)
	v_mfma_f32_32x32x16_bf16 v[50:65], v[94:97], v[142:145], v[50:65]
	ds_read_b128 v[82:85], v221 offset:8192
	ds_read_b128 v[86:89], v222 offset:8192
	ds_read_b128 v[90:93], v223 offset:8192
	ds_read_b128 v[94:97], v224 offset:8192
	s_waitcnt lgkmcnt(7)
	v_mfma_f32_32x32x16_bf16 v[2:17], v[98:101], v[130:133], 0
	s_waitcnt lgkmcnt(6)
	v_mfma_f32_32x32x16_bf16 v[2:17], v[102:105], v[134:137], v[2:17]
	s_waitcnt lgkmcnt(5)
	v_mfma_f32_32x32x16_bf16 v[2:17], v[106:109], v[138:141], v[2:17]
	s_waitcnt lgkmcnt(4)
	v_mfma_f32_32x32x16_bf16 v[2:17], v[110:113], v[142:145], v[2:17]
	ds_read_b128 v[98:101], v221 offset:12288
	ds_read_b128 v[102:105], v222 offset:12288
	ds_read_b128 v[106:109], v223 offset:12288
	ds_read_b128 v[110:113], v224 offset:12288
	s_waitcnt lgkmcnt(7)
	v_mfma_f32_32x32x16_bf16 v[34:49], v[82:85], v[130:133], 0
	s_waitcnt lgkmcnt(6)
	v_mfma_f32_32x32x16_bf16 v[34:49], v[86:89], v[134:137], v[34:49]
	s_waitcnt lgkmcnt(5)
	v_mfma_f32_32x32x16_bf16 v[34:49], v[90:93], v[138:141], v[34:49]
	s_waitcnt lgkmcnt(4)
	v_mfma_f32_32x32x16_bf16 v[34:49], v[94:97], v[142:145], v[34:49]
	ds_read_b128 v[82:85], v221 offset:16384
	ds_read_b128 v[86:89], v222 offset:16384
	ds_read_b128 v[90:93], v223 offset:16384
	ds_read_b128 v[94:97], v224 offset:16384
	s_waitcnt lgkmcnt(7)
	v_mfma_f32_32x32x16_bf16 v[18:33], v[98:101], v[130:133], 0
	s_waitcnt lgkmcnt(6)
	v_mfma_f32_32x32x16_bf16 v[18:33], v[102:105], v[134:137], v[18:33]
	s_waitcnt lgkmcnt(5)
	v_mfma_f32_32x32x16_bf16 v[18:33], v[106:109], v[138:141], v[18:33]
	s_waitcnt lgkmcnt(4)
	v_mfma_f32_32x32x16_bf16 v[18:33], v[110:113], v[142:145], v[18:33]
	s_waitcnt lgkmcnt(3)
	v_mfma_f32_32x32x16_bf16 v[66:81], v[82:85], v[130:133], 0
	s_waitcnt lgkmcnt(2)
	v_mfma_f32_32x32x16_bf16 v[66:81], v[86:89], v[134:137], v[66:81]
	s_waitcnt lgkmcnt(1)
	v_mfma_f32_32x32x16_bf16 v[66:81], v[90:93], v[138:141], v[66:81]
	s_waitcnt lgkmcnt(0)
	v_mfma_f32_32x32x16_bf16 v[66:81], v[94:97], v[142:145], v[66:81]
	s_branch .LBB0_174

.LBB0_164:
	s_lshl_b32 s25, s22, 8
	s_add_i32 s25, s25, s23
	s_ashr_i32 s6, s25, 5
	s_sub_i32 s6, 4, s6
	s_cmpk_lt_i32 s25, 0x80
	s_cselect_b32 s19, s6, 0
	s_cmp_lt_i32 s19, 1
	s_cselect_b64 s[76:77], -1, 0
	s_cmp_eq_u32 s19, 0
	s_cbranch_scc1 .Lqk_fast
	s_cmp_gt_i32 s19, 0
	s_cbranch_scc1 .Lattn_neg0
	ds_read_b128 v[4:7], v221
	s_waitcnt vmcnt(3) lgkmcnt(0)
	v_mfma_f32_32x32x16_bf16 v[50:65], v[4:7], v[130:133], 0
	ds_read_b128 v[4:7], v222
	s_waitcnt vmcnt(2) lgkmcnt(0)
	v_mfma_f32_32x32x16_bf16 v[50:65], v[4:7], v[134:137], v[50:65]
	ds_read_b128 v[4:7], v223
	s_waitcnt vmcnt(1) lgkmcnt(0)
	v_mfma_f32_32x32x16_bf16 v[50:65], v[4:7], v[138:141], v[50:65]
	ds_read_b128 v[4:7], v224
	s_waitcnt vmcnt(0) lgkmcnt(0)
	v_mfma_f32_32x32x16_bf16 v[50:65], v[4:7], v[142:145], v[50:65]

.LBB0_205:
	ds_read_b64_tr_b16 v[238:239], v183 offset:49152
	ds_read_b64_tr_b16 v[240:241], v183 offset:49664
	ds_read_b64_tr_b16 v[242:243], v184 offset:24576
	ds_read_b64_tr_b16 v[244:245], v184 offset:25088
	ds_read_b64_tr_b16 v[246:247], v183 offset:50176
	ds_read_b64_tr_b16 v[248:249], v183 offset:50688
	ds_read_b64_tr_b16 v[250:251], v184 offset:25600
	ds_read_b64_tr_b16 v[252:253], v184 offset:26112
	s_waitcnt lgkmcnt(6)
	v_mfma_f32_32x32x16_bf16 v[32:47], v[6:9], v[238:241], 0
	ds_read_b64_tr_b16 v[238:239], v183 offset:51200
	ds_read_b64_tr_b16 v[240:241], v183 offset:51712
	s_waitcnt lgkmcnt(6)
	v_mfma_f32_32x32x16_bf16 v[16:31], v[6:9], v[242:245], 0
	ds_read_b64_tr_b16 v[242:243], v184 offset:26624
	ds_read_b64_tr_b16 v[244:245], v184 offset:27136
	s_waitcnt lgkmcnt(6)
	v_mfma_f32_32x32x16_bf16 v[32:47], v[2:5], v[246:249], v[32:47]
	ds_read_b64_tr_b16 v[246:247], v183 offset:52224
	ds_read_b64_tr_b16 v[248:249], v183 offset:52736
	s_waitcnt lgkmcnt(6)
	v_mfma_f32_32x32x16_bf16 v[16:31], v[2:5], v[250:253], v[16:31]
	ds_read_b64_tr_b16 v[250:251], v184 offset:27648
	ds_read_b64_tr_b16 v[252:253], v184 offset:28160
	s_waitcnt lgkmcnt(6)
	v_mfma_f32_32x32x16_bf16 v[32:47], v[76:79], v[238:241], v[32:47]
	ds_read_b64_tr_b16 v[238:239], v183 offset:53248
	ds_read_b64_tr_b16 v[240:241], v183 offset:53760
	s_waitcnt lgkmcnt(6)
	v_mfma_f32_32x32x16_bf16 v[16:31], v[76:79], v[242:245], v[16:31]
	ds_read_b64_tr_b16 v[242:243], v184 offset:28672
	ds_read_b64_tr_b16 v[244:245], v184 offset:29184
	s_waitcnt lgkmcnt(6)
	v_mfma_f32_32x32x16_bf16 v[32:47], v[72:75], v[246:249], v[32:47]
	ds_read_b64_tr_b16 v[246:247], v183 offset:54272
	ds_read_b64_tr_b16 v[248:249], v183 offset:54784
	s_waitcnt lgkmcnt(6)
	v_mfma_f32_32x32x16_bf16 v[16:31], v[72:75], v[250:253], v[16:31]
	ds_read_b64_tr_b16 v[250:251], v184 offset:29696
	ds_read_b64_tr_b16 v[252:253], v184 offset:30208
	s_waitcnt lgkmcnt(6)
	v_mfma_f32_32x32x16_bf16 v[32:47], v[68:71], v[238:241], v[32:47]
	ds_read_b64_tr_b16 v[238:239], v183 offset:55296
	ds_read_b64_tr_b16 v[240:241], v183 offset:55808
	s_waitcnt lgkmcnt(6)
	v_mfma_f32_32x32x16_bf16 v[16:31], v[68:71], v[242:245], v[16:31]
	ds_read_b64_tr_b16 v[242:243], v184 offset:30720
	ds_read_b64_tr_b16 v[244:245], v184 offset:31232
	s_waitcnt lgkmcnt(6)
	v_mfma_f32_32x32x16_bf16 v[32:47], v[64:67], v[246:249], v[32:47]
	ds_read_b64_tr_b16 v[246:247], v183 offset:56320
	ds_read_b64_tr_b16 v[248:249], v183 offset:56832
	s_waitcnt lgkmcnt(6)
	v_mfma_f32_32x32x16_bf16 v[16:31], v[64:67], v[250:253], v[16:31]
	ds_read_b64_tr_b16 v[250:251], v184 offset:31744
	ds_read_b64_tr_b16 v[252:253], v184 offset:32256
	s_waitcnt lgkmcnt(6)
	v_mfma_f32_32x32x16_bf16 v[32:47], v[60:63], v[238:241], v[32:47]
	ds_read_b64_tr_b16 v[238:239], v183 offset:57344
	ds_read_b64_tr_b16 v[240:241], v183 offset:57856
	s_waitcnt lgkmcnt(6)
	v_mfma_f32_32x32x16_bf16 v[16:31], v[60:63], v[242:245], v[16:31]
	ds_read_b64_tr_b16 v[242:243], v184 offset:32768
	ds_read_b64_tr_b16 v[244:245], v184 offset:33280
	s_waitcnt lgkmcnt(6)
	v_mfma_f32_32x32x16_bf16 v[32:47], v[56:59], v[246:249], v[32:47]
	ds_read_b64_tr_b16 v[246:247], v183 offset:58368
	ds_read_b64_tr_b16 v[248:249], v183 offset:58880
	s_waitcnt lgkmcnt(6)
	v_mfma_f32_32x32x16_bf16 v[16:31], v[56:59], v[250:253], v[16:31]
	ds_read_b64_tr_b16 v[250:251], v184 offset:33792
	ds_read_b64_tr_b16 v[252:253], v184 offset:34304
	s_waitcnt lgkmcnt(6)
	v_mfma_f32_32x32x16_bf16 v[32:47], v[52:55], v[238:241], v[32:47]
	s_waitcnt lgkmcnt(4)
	v_mfma_f32_32x32x16_bf16 v[16:31], v[52:55], v[242:245], v[16:31]
	s_waitcnt lgkmcnt(2)
	v_mfma_f32_32x32x16_bf16 v[32:47], v[48:51], v[246:249], v[32:47]
	s_waitcnt lgkmcnt(0)
	v_mfma_f32_32x32x16_bf16 v[16:31], v[48:51], v[250:253], v[16:31]
	s_mov_b64 s[76:77], 0x40000
	s_branch .LBB0_213

.LBB0_382:
	s_waitcnt vmcnt(0)
	v_lshl_or_b32 v144, s29, 7, v156
	v_lshl_add_u32 v164, s28, 8, v1
	v_ashrrev_i32_e32 v145, 31, v144
	v_mov_b64_e32 v[142:143], s[82:83]
	s_movk_i32 s21, 0x1600
	v_mad_i64_i32 v[146:147], s[28:29], v164, s21, v[142:143]
	v_lshlrev_b64 v[144:145], 1, v[144:145]
	v_mov_b32_e32 v168, 1.0
	v_lshl_add_u64 v[146:147], v[146:147], 0, v[144:145]
	s_andn2_b64 vcc, exec, s[6:7]
	v_cvt_f32_u32_e32 v166, v166
	v_fmamk_f32 v166, v166, 0x34800000, v228
	v_rsq_f32_e32 v166, v166
	v_pk_mul_f32 v[122:123], v[126:127], v[122:123]
	v_pk_mul_f32 v[124:125], v[128:129], v[124:125]
	v_pk_mul_f32 v[114:115], v[118:119], v[114:115]
	v_pk_mul_f32 v[116:117], v[120:121], v[116:117]
	v_mul_f32_e32 v172, 0xbfb8aa3b, v166
	v_mul_f32_e32 v170, v166, v166
	v_pk_mul_f32 v[126:127], v[126:127], v[172:173] op_sel_hi:[1,0]
	v_pk_mul_f32 v[128:129], v[128:129], v[172:173] op_sel_hi:[1,0]
	v_pk_mul_f32 v[118:119], v[118:119], v[172:173] op_sel_hi:[1,0]
	v_pk_mul_f32 v[120:121], v[120:121], v[172:173] op_sel_hi:[1,0]
	v_exp_f32_e32 v126, v126
	v_exp_f32_e32 v127, v127
	v_exp_f32_e32 v128, v128
	v_exp_f32_e32 v129, v129
	v_exp_f32_e32 v118, v118
	v_exp_f32_e32 v119, v119
	v_exp_f32_e32 v120, v120
	v_exp_f32_e32 v121, v121
	v_pk_add_f32 v[126:127], v[126:127], v[168:169] op_sel_hi:[1,0]
	v_pk_add_f32 v[128:129], v[128:129], v[168:169] op_sel_hi:[1,0]
	v_pk_add_f32 v[118:119], v[118:119], v[168:169] op_sel_hi:[1,0]
	v_pk_add_f32 v[120:121], v[120:121], v[168:169] op_sel_hi:[1,0]
	v_rcp_f32_e32 v126, v126
	v_rcp_f32_e32 v127, v127
	v_rcp_f32_e32 v128, v128
	v_rcp_f32_e32 v129, v129
	v_rcp_f32_e32 v118, v118
	v_rcp_f32_e32 v119, v119
	v_rcp_f32_e32 v120, v120
	v_rcp_f32_e32 v121, v121
	v_pk_mul_f32 v[122:123], v[122:123], v[170:171] op_sel_hi:[1,0]
	v_pk_mul_f32 v[124:125], v[124:125], v[170:171] op_sel_hi:[1,0]
	v_pk_mul_f32 v[114:115], v[114:115], v[170:171] op_sel_hi:[1,0]
	v_pk_mul_f32 v[116:117], v[116:117], v[170:171] op_sel_hi:[1,0]
	v_pk_mul_f32 v[122:123], v[122:123], v[126:127]
	v_pk_mul_f32 v[124:125], v[124:125], v[128:129]
	v_pk_mul_f32 v[118:119], v[114:115], v[118:119]
	v_pk_mul_f32 v[120:121], v[116:117], v[120:121]
	v_cvt_pk_bf16_f32 v114, v122, v123
	v_cvt_pk_bf16_f32 v115, v124, v125
	v_cvt_pk_bf16_f32 v116, v118, v119
	v_cvt_pk_bf16_f32 v117, v120, v121
	global_store_dwordx4 v[146:147], v[114:117], off sc1
	s_nop 1
	v_cvt_f32_u32_e32 v165, v165
	v_fmamk_f32 v165, v165, 0x34800000, v228
	v_rsq_f32_e32 v165, v165
	v_pk_mul_f32 v[106:107], v[110:111], v[106:107]
	v_pk_mul_f32 v[108:109], v[112:113], v[108:109]
	v_pk_mul_f32 v[98:99], v[102:103], v[98:99]
	v_pk_mul_f32 v[100:101], v[104:105], v[100:101]
	v_mul_f32_e32 v172, 0xbfb8aa3b, v165
	v_mul_f32_e32 v170, v165, v165
	v_pk_mul_f32 v[110:111], v[110:111], v[172:173] op_sel_hi:[1,0]
	v_pk_mul_f32 v[112:113], v[112:113], v[172:173] op_sel_hi:[1,0]
	v_pk_mul_f32 v[102:103], v[102:103], v[172:173] op_sel_hi:[1,0]
	v_pk_mul_f32 v[104:105], v[104:105], v[172:173] op_sel_hi:[1,0]
	v_exp_f32_e32 v110, v110
	v_exp_f32_e32 v111, v111
	v_exp_f32_e32 v112, v112
	v_exp_f32_e32 v113, v113
	v_exp_f32_e32 v102, v102
	v_exp_f32_e32 v103, v103
	v_exp_f32_e32 v104, v104
	v_exp_f32_e32 v105, v105
	v_or_b32_e32 v114, 16, v164
	v_mad_i64_i32 v[114:115], s[28:29], v114, s21, v[142:143]
	v_lshl_add_u64 v[114:115], v[114:115], 0, v[144:145]
	v_pk_add_f32 v[110:111], v[110:111], v[168:169] op_sel_hi:[1,0]
	v_pk_add_f32 v[112:113], v[112:113], v[168:169] op_sel_hi:[1,0]
	v_pk_add_f32 v[102:103], v[102:103], v[168:169] op_sel_hi:[1,0]
	v_pk_add_f32 v[104:105], v[104:105], v[168:169] op_sel_hi:[1,0]
	v_rcp_f32_e32 v110, v110
	v_rcp_f32_e32 v111, v111
	v_rcp_f32_e32 v112, v112
	v_rcp_f32_e32 v113, v113
	v_rcp_f32_e32 v102, v102
	v_rcp_f32_e32 v103, v103
	v_rcp_f32_e32 v104, v104
	v_rcp_f32_e32 v105, v105
	v_pk_mul_f32 v[106:107], v[106:107], v[170:171] op_sel_hi:[1,0]
	v_pk_mul_f32 v[108:109], v[108:109], v[170:171] op_sel_hi:[1,0]
	v_pk_mul_f32 v[98:99], v[98:99], v[170:171] op_sel_hi:[1,0]
	v_pk_mul_f32 v[100:101], v[100:101], v[170:171] op_sel_hi:[1,0]
	v_pk_mul_f32 v[106:107], v[106:107], v[110:111]
	v_pk_mul_f32 v[108:109], v[108:109], v[112:113]
	v_pk_mul_f32 v[102:103], v[98:99], v[102:103]
	v_pk_mul_f32 v[104:105], v[100:101], v[104:105]
	v_cvt_pk_bf16_f32 v98, v106, v107
	v_cvt_pk_bf16_f32 v99, v108, v109
	v_cvt_pk_bf16_f32 v100, v102, v103
	v_cvt_pk_bf16_f32 v101, v104, v105
	global_store_dwordx4 v[114:115], v[98:101], off sc1
	s_nop 1
	v_cvt_f32_u32_e32 v163, v163
	v_fmamk_f32 v163, v163, 0x34800000, v228
	v_rsq_f32_e32 v163, v163
	v_pk_mul_f32 v[90:91], v[94:95], v[90:91]
	v_pk_mul_f32 v[92:93], v[96:97], v[92:93]
	v_pk_mul_f32 v[82:83], v[86:87], v[82:83]
	v_pk_mul_f32 v[84:85], v[88:89], v[84:85]
	v_mul_f32_e32 v172, 0xbfb8aa3b, v163
	v_mul_f32_e32 v170, v163, v163
	v_pk_mul_f32 v[94:95], v[94:95], v[172:173] op_sel_hi:[1,0]
	v_pk_mul_f32 v[96:97], v[96:97], v[172:173] op_sel_hi:[1,0]
	v_pk_mul_f32 v[86:87], v[86:87], v[172:173] op_sel_hi:[1,0]
	v_pk_mul_f32 v[88:89], v[88:89], v[172:173] op_sel_hi:[1,0]
	v_exp_f32_e32 v94, v94
	v_exp_f32_e32 v95, v95
	v_exp_f32_e32 v96, v96
	v_exp_f32_e32 v97, v97
	v_exp_f32_e32 v86, v86
	v_exp_f32_e32 v87, v87
	v_exp_f32_e32 v88, v88
	v_exp_f32_e32 v89, v89
	v_or_b32_e32 v98, 32, v164
	v_mad_i64_i32 v[98:99], s[28:29], v98, s21, v[142:143]
	v_lshl_add_u64 v[98:99], v[98:99], 0, v[144:145]
	v_pk_add_f32 v[94:95], v[94:95], v[168:169] op_sel_hi:[1,0]
	v_pk_add_f32 v[96:97], v[96:97], v[168:169] op_sel_hi:[1,0]
	v_pk_add_f32 v[86:87], v[86:87], v[168:169] op_sel_hi:[1,0]
	v_pk_add_f32 v[88:89], v[88:89], v[168:169] op_sel_hi:[1,0]
	v_rcp_f32_e32 v94, v94
	v_rcp_f32_e32 v95, v95
	v_rcp_f32_e32 v96, v96
	v_rcp_f32_e32 v97, v97
	v_rcp_f32_e32 v86, v86
	v_rcp_f32_e32 v87, v87
	v_rcp_f32_e32 v88, v88
	v_rcp_f32_e32 v89, v89
	v_pk_mul_f32 v[90:91], v[90:91], v[170:171] op_sel_hi:[1,0]
	v_pk_mul_f32 v[92:93], v[92:93], v[170:171] op_sel_hi:[1,0]
	v_pk_mul_f32 v[82:83], v[82:83], v[170:171] op_sel_hi:[1,0]
	v_pk_mul_f32 v[84:85], v[84:85], v[170:171] op_sel_hi:[1,0]
	v_pk_mul_f32 v[90:91], v[90:91], v[94:95]
	v_pk_mul_f32 v[92:93], v[92:93], v[96:97]
	v_pk_mul_f32 v[86:87], v[82:83], v[86:87]
	v_pk_mul_f32 v[88:89], v[84:85], v[88:89]
	v_cvt_pk_bf16_f32 v82, v90, v91
	v_cvt_pk_bf16_f32 v83, v92, v93
	v_cvt_pk_bf16_f32 v84, v86, v87
	v_cvt_pk_bf16_f32 v85, v88, v89
	global_store_dwordx4 v[98:99], v[82:85], off sc1
	s_nop 1
	v_cvt_f32_u32_e32 v162, v162
	v_fmamk_f32 v162, v162, 0x34800000, v228
	v_rsq_f32_e32 v162, v162
	v_pk_mul_f32 v[74:75], v[78:79], v[74:75]
	v_pk_mul_f32 v[76:77], v[80:81], v[76:77]
	v_pk_mul_f32 v[66:67], v[70:71], v[66:67]
	v_pk_mul_f32 v[68:69], v[72:73], v[68:69]
	v_mul_f32_e32 v172, 0xbfb8aa3b, v162
	v_mul_f32_e32 v170, v162, v162
	v_pk_mul_f32 v[78:79], v[78:79], v[172:173] op_sel_hi:[1,0]
	v_pk_mul_f32 v[80:81], v[80:81], v[172:173] op_sel_hi:[1,0]
	v_pk_mul_f32 v[70:71], v[70:71], v[172:173] op_sel_hi:[1,0]
	v_pk_mul_f32 v[72:73], v[72:73], v[172:173] op_sel_hi:[1,0]
	v_exp_f32_e32 v78, v78
	v_exp_f32_e32 v79, v79
	v_exp_f32_e32 v80, v80
	v_exp_f32_e32 v81, v81
	v_exp_f32_e32 v70, v70
	v_exp_f32_e32 v71, v71
	v_exp_f32_e32 v72, v72
	v_exp_f32_e32 v73, v73
	v_or_b32_e32 v82, 48, v164
	v_mad_i64_i32 v[82:83], s[28:29], v82, s21, v[142:143]
	v_lshl_add_u64 v[82:83], v[82:83], 0, v[144:145]
	v_pk_add_f32 v[78:79], v[78:79], v[168:169] op_sel_hi:[1,0]
	v_pk_add_f32 v[80:81], v[80:81], v[168:169] op_sel_hi:[1,0]
	v_pk_add_f32 v[70:71], v[70:71], v[168:169] op_sel_hi:[1,0]
	v_pk_add_f32 v[72:73], v[72:73], v[168:169] op_sel_hi:[1,0]
	v_rcp_f32_e32 v78, v78
	v_rcp_f32_e32 v79, v79
	v_rcp_f32_e32 v80, v80
	v_rcp_f32_e32 v81, v81
	v_rcp_f32_e32 v70, v70
	v_rcp_f32_e32 v71, v71
	v_rcp_f32_e32 v72, v72
	v_rcp_f32_e32 v73, v73
	v_pk_mul_f32 v[74:75], v[74:75], v[170:171] op_sel_hi:[1,0]
	v_pk_mul_f32 v[76:77], v[76:77], v[170:171] op_sel_hi:[1,0]
	v_pk_mul_f32 v[66:67], v[66:67], v[170:171] op_sel_hi:[1,0]
	v_pk_mul_f32 v[68:69], v[68:69], v[170:171] op_sel_hi:[1,0]
	v_pk_mul_f32 v[74:75], v[74:75], v[78:79]
	v_pk_mul_f32 v[76:77], v[76:77], v[80:81]
	v_pk_mul_f32 v[70:71], v[66:67], v[70:71]
	v_pk_mul_f32 v[72:73], v[68:69], v[72:73]
	v_cvt_pk_bf16_f32 v66, v74, v75
	v_cvt_pk_bf16_f32 v67, v76, v77
	v_cvt_pk_bf16_f32 v68, v70, v71
	v_cvt_pk_bf16_f32 v69, v72, v73
	global_store_dwordx4 v[82:83], v[66:69], off sc1
	s_nop 1
	v_cvt_f32_u32_e32 v161, v161
	v_fmamk_f32 v161, v161, 0x34800000, v228
	v_rsq_f32_e32 v161, v161
	v_pk_mul_f32 v[58:59], v[62:63], v[58:59]
	v_pk_mul_f32 v[60:61], v[64:65], v[60:61]
	v_pk_mul_f32 v[50:51], v[54:55], v[50:51]
	v_pk_mul_f32 v[52:53], v[56:57], v[52:53]
	v_mul_f32_e32 v172, 0xbfb8aa3b, v161
	v_mul_f32_e32 v170, v161, v161
	v_pk_mul_f32 v[62:63], v[62:63], v[172:173] op_sel_hi:[1,0]
	v_pk_mul_f32 v[64:65], v[64:65], v[172:173] op_sel_hi:[1,0]
	v_pk_mul_f32 v[54:55], v[54:55], v[172:173] op_sel_hi:[1,0]
	v_pk_mul_f32 v[56:57], v[56:57], v[172:173] op_sel_hi:[1,0]
	v_exp_f32_e32 v62, v62
	v_exp_f32_e32 v63, v63
	v_exp_f32_e32 v64, v64
	v_exp_f32_e32 v65, v65
	v_exp_f32_e32 v54, v54
	v_exp_f32_e32 v55, v55
	v_exp_f32_e32 v56, v56
	v_exp_f32_e32 v57, v57
	v_add_u32_e32 v66, 0x80, v164
	v_mad_i64_i32 v[66:67], s[28:29], v66, s21, v[142:143]
	v_lshl_add_u64 v[66:67], v[66:67], 0, v[144:145]
	v_pk_add_f32 v[62:63], v[62:63], v[168:169] op_sel_hi:[1,0]
	v_pk_add_f32 v[64:65], v[64:65], v[168:169] op_sel_hi:[1,0]
	v_pk_add_f32 v[54:55], v[54:55], v[168:169] op_sel_hi:[1,0]
	v_pk_add_f32 v[56:57], v[56:57], v[168:169] op_sel_hi:[1,0]
	v_rcp_f32_e32 v62, v62
	v_rcp_f32_e32 v63, v63
	v_rcp_f32_e32 v64, v64
	v_rcp_f32_e32 v65, v65
	v_rcp_f32_e32 v54, v54
	v_rcp_f32_e32 v55, v55
	v_rcp_f32_e32 v56, v56
	v_rcp_f32_e32 v57, v57
	v_pk_mul_f32 v[58:59], v[58:59], v[170:171] op_sel_hi:[1,0]
	v_pk_mul_f32 v[60:61], v[60:61], v[170:171] op_sel_hi:[1,0]
	v_pk_mul_f32 v[50:51], v[50:51], v[170:171] op_sel_hi:[1,0]
	v_pk_mul_f32 v[52:53], v[52:53], v[170:171] op_sel_hi:[1,0]
	v_pk_mul_f32 v[58:59], v[58:59], v[62:63]
	v_pk_mul_f32 v[60:61], v[60:61], v[64:65]
	v_pk_mul_f32 v[54:55], v[50:51], v[54:55]
	v_pk_mul_f32 v[56:57], v[52:53], v[56:57]
	v_cvt_pk_bf16_f32 v50, v58, v59
	v_cvt_pk_bf16_f32 v51, v60, v61
	v_cvt_pk_bf16_f32 v52, v54, v55
	v_cvt_pk_bf16_f32 v53, v56, v57
	global_store_dwordx4 v[66:67], v[50:53], off sc1
	s_nop 1
	v_cvt_f32_u32_e32 v160, v160
	v_fmamk_f32 v160, v160, 0x34800000, v228
	v_rsq_f32_e32 v160, v160
	v_pk_mul_f32 v[42:43], v[46:47], v[42:43]
	v_pk_mul_f32 v[44:45], v[48:49], v[44:45]
	v_pk_mul_f32 v[34:35], v[38:39], v[34:35]
	v_pk_mul_f32 v[36:37], v[40:41], v[36:37]
	v_mul_f32_e32 v172, 0xbfb8aa3b, v160
	v_mul_f32_e32 v170, v160, v160
	v_pk_mul_f32 v[46:47], v[46:47], v[172:173] op_sel_hi:[1,0]
	v_pk_mul_f32 v[48:49], v[48:49], v[172:173] op_sel_hi:[1,0]
	v_pk_mul_f32 v[38:39], v[38:39], v[172:173] op_sel_hi:[1,0]
	v_pk_mul_f32 v[40:41], v[40:41], v[172:173] op_sel_hi:[1,0]
	v_exp_f32_e32 v46, v46
	v_exp_f32_e32 v47, v47
	v_exp_f32_e32 v48, v48
	v_exp_f32_e32 v49, v49
	v_exp_f32_e32 v38, v38
	v_exp_f32_e32 v39, v39
	v_exp_f32_e32 v40, v40
	v_exp_f32_e32 v41, v41
	v_add_u32_e32 v50, 0x90, v164
	v_mad_i64_i32 v[50:51], s[28:29], v50, s21, v[142:143]
	v_lshl_add_u64 v[50:51], v[50:51], 0, v[144:145]
	v_pk_add_f32 v[46:47], v[46:47], v[168:169] op_sel_hi:[1,0]
	v_pk_add_f32 v[48:49], v[48:49], v[168:169] op_sel_hi:[1,0]
	v_pk_add_f32 v[38:39], v[38:39], v[168:169] op_sel_hi:[1,0]
	v_pk_add_f32 v[40:41], v[40:41], v[168:169] op_sel_hi:[1,0]
	v_rcp_f32_e32 v46, v46
	v_rcp_f32_e32 v47, v47
	v_rcp_f32_e32 v48, v48
	v_rcp_f32_e32 v49, v49
	v_rcp_f32_e32 v38, v38
	v_rcp_f32_e32 v39, v39
	v_rcp_f32_e32 v40, v40
	v_rcp_f32_e32 v41, v41
	v_pk_mul_f32 v[42:43], v[42:43], v[170:171] op_sel_hi:[1,0]
	v_pk_mul_f32 v[44:45], v[44:45], v[170:171] op_sel_hi:[1,0]
	v_pk_mul_f32 v[34:35], v[34:35], v[170:171] op_sel_hi:[1,0]
	v_pk_mul_f32 v[36:37], v[36:37], v[170:171] op_sel_hi:[1,0]
	v_pk_mul_f32 v[42:43], v[42:43], v[46:47]
	v_pk_mul_f32 v[44:45], v[44:45], v[48:49]
	v_pk_mul_f32 v[38:39], v[34:35], v[38:39]
	v_pk_mul_f32 v[40:41], v[36:37], v[40:41]
	v_cvt_pk_bf16_f32 v34, v42, v43
	v_cvt_pk_bf16_f32 v35, v44, v45
	v_cvt_pk_bf16_f32 v36, v38, v39
	v_cvt_pk_bf16_f32 v37, v40, v41
	global_store_dwordx4 v[50:51], v[34:37], off sc1
	s_nop 1
	v_cvt_f32_u32_e32 v159, v159
	v_fmamk_f32 v159, v159, 0x34800000, v228
	v_rsq_f32_e32 v159, v159
	v_pk_mul_f32 v[26:27], v[30:31], v[26:27]
	v_pk_mul_f32 v[28:29], v[32:33], v[28:29]
	v_pk_mul_f32 v[18:19], v[22:23], v[18:19]
	v_pk_mul_f32 v[20:21], v[24:25], v[20:21]
	v_mul_f32_e32 v172, 0xbfb8aa3b, v159
	v_mul_f32_e32 v170, v159, v159
	v_pk_mul_f32 v[30:31], v[30:31], v[172:173] op_sel_hi:[1,0]
	v_pk_mul_f32 v[32:33], v[32:33], v[172:173] op_sel_hi:[1,0]
	v_pk_mul_f32 v[22:23], v[22:23], v[172:173] op_sel_hi:[1,0]
	v_pk_mul_f32 v[24:25], v[24:25], v[172:173] op_sel_hi:[1,0]
	v_exp_f32_e32 v30, v30
	v_exp_f32_e32 v31, v31
	v_exp_f32_e32 v32, v32
	v_exp_f32_e32 v33, v33
	v_exp_f32_e32 v22, v22
	v_exp_f32_e32 v23, v23
	v_exp_f32_e32 v24, v24
	v_exp_f32_e32 v25, v25
	v_add_u32_e32 v34, 0xa0, v164
	v_mad_i64_i32 v[34:35], s[28:29], v34, s21, v[142:143]
	v_lshl_add_u64 v[34:35], v[34:35], 0, v[144:145]
	v_pk_add_f32 v[30:31], v[30:31], v[168:169] op_sel_hi:[1,0]
	v_pk_add_f32 v[32:33], v[32:33], v[168:169] op_sel_hi:[1,0]
	v_pk_add_f32 v[22:23], v[22:23], v[168:169] op_sel_hi:[1,0]
	v_pk_add_f32 v[24:25], v[24:25], v[168:169] op_sel_hi:[1,0]
	v_rcp_f32_e32 v30, v30
	v_rcp_f32_e32 v31, v31
	v_rcp_f32_e32 v32, v32
	v_rcp_f32_e32 v33, v33
	v_rcp_f32_e32 v22, v22
	v_rcp_f32_e32 v23, v23
	v_rcp_f32_e32 v24, v24
	v_rcp_f32_e32 v25, v25
	v_pk_mul_f32 v[26:27], v[26:27], v[170:171] op_sel_hi:[1,0]
	v_pk_mul_f32 v[28:29], v[28:29], v[170:171] op_sel_hi:[1,0]
	v_pk_mul_f32 v[18:19], v[18:19], v[170:171] op_sel_hi:[1,0]
	v_pk_mul_f32 v[20:21], v[20:21], v[170:171] op_sel_hi:[1,0]
	v_pk_mul_f32 v[26:27], v[26:27], v[30:31]
	v_pk_mul_f32 v[28:29], v[28:29], v[32:33]
	v_pk_mul_f32 v[22:23], v[18:19], v[22:23]
	v_pk_mul_f32 v[24:25], v[20:21], v[24:25]
	v_cvt_pk_bf16_f32 v18, v26, v27
	v_cvt_pk_bf16_f32 v19, v28, v29
	v_cvt_pk_bf16_f32 v20, v22, v23
	v_cvt_pk_bf16_f32 v21, v24, v25
	global_store_dwordx4 v[34:35], v[18:21], off sc1
	s_nop 1
	v_cvt_f32_u32_e32 v158, v158
	v_fmamk_f32 v158, v158, 0x34800000, v228
	v_rsq_f32_e32 v158, v158
	v_pk_mul_f32 v[10:11], v[14:15], v[10:11]
	v_pk_mul_f32 v[12:13], v[16:17], v[12:13]
	v_pk_mul_f32 v[2:3], v[6:7], v[2:3]
	v_pk_mul_f32 v[4:5], v[8:9], v[4:5]
	v_mul_f32_e32 v172, 0xbfb8aa3b, v158
	v_mul_f32_e32 v170, v158, v158
	v_pk_mul_f32 v[14:15], v[14:15], v[172:173] op_sel_hi:[1,0]
	v_pk_mul_f32 v[16:17], v[16:17], v[172:173] op_sel_hi:[1,0]
	v_pk_mul_f32 v[6:7], v[6:7], v[172:173] op_sel_hi:[1,0]
	v_pk_mul_f32 v[8:9], v[8:9], v[172:173] op_sel_hi:[1,0]
	v_exp_f32_e32 v14, v14
	v_exp_f32_e32 v15, v15
	v_exp_f32_e32 v16, v16
	v_exp_f32_e32 v17, v17
	v_exp_f32_e32 v6, v6
	v_exp_f32_e32 v7, v7
	v_exp_f32_e32 v8, v8
	v_exp_f32_e32 v9, v9
	v_add_u32_e32 v18, 0xb0, v164
	v_mad_i64_i32 v[18:19], s[28:29], v18, s21, v[142:143]
	v_lshl_add_u64 v[18:19], v[18:19], 0, v[144:145]
	v_pk_add_f32 v[14:15], v[14:15], v[168:169] op_sel_hi:[1,0]
	v_pk_add_f32 v[16:17], v[16:17], v[168:169] op_sel_hi:[1,0]
	v_pk_add_f32 v[6:7], v[6:7], v[168:169] op_sel_hi:[1,0]
	v_pk_add_f32 v[8:9], v[8:9], v[168:169] op_sel_hi:[1,0]
	v_rcp_f32_e32 v14, v14
	v_rcp_f32_e32 v15, v15
	v_rcp_f32_e32 v16, v16
	v_rcp_f32_e32 v17, v17
	v_rcp_f32_e32 v6, v6
	v_rcp_f32_e32 v7, v7
	v_rcp_f32_e32 v8, v8
	v_rcp_f32_e32 v9, v9
	v_pk_mul_f32 v[10:11], v[10:11], v[170:171] op_sel_hi:[1,0]
	v_pk_mul_f32 v[12:13], v[12:13], v[170:171] op_sel_hi:[1,0]
	v_pk_mul_f32 v[2:3], v[2:3], v[170:171] op_sel_hi:[1,0]
	v_pk_mul_f32 v[4:5], v[4:5], v[170:171] op_sel_hi:[1,0]
	v_pk_mul_f32 v[10:11], v[10:11], v[14:15]
	v_pk_mul_f32 v[12:13], v[12:13], v[16:17]
	v_pk_mul_f32 v[6:7], v[2:3], v[6:7]
	v_pk_mul_f32 v[8:9], v[4:5], v[8:9]
	v_cvt_pk_bf16_f32 v2, v10, v11
	v_cvt_pk_bf16_f32 v3, v12, v13
	v_cvt_pk_bf16_f32 v4, v6, v7
	v_cvt_pk_bf16_f32 v5, v8, v9
	global_store_dwordx4 v[18:19], v[2:5], off sc1
	s_nop 1
	s_mov_b64 s[28:29], -1
	s_cbranch_vccnz .LBB0_359
	s_lshl_b32 s6, s22, 8
	v_add_u32_e32 v2, s6, v1
	v_ashrrev_i32_e32 v3, 31, v2
	v_lshl_add_u64 v[2:3], v[2:3], 2, s[12:13]
	global_load_dword v166, v[2:3], off
	v_add_u32_e32 v2, s6, v148
	v_ashrrev_i32_e32 v3, 31, v2
	v_lshl_add_u64 v[2:3], v[2:3], 2, s[12:13]
	global_load_dword v165, v[2:3], off
	v_add_u32_e32 v2, s6, v149
	v_ashrrev_i32_e32 v3, 31, v2
	v_lshl_add_u64 v[2:3], v[2:3], 2, s[12:13]
	global_load_dword v163, v[2:3], off
	v_add_u32_e32 v2, s6, v150
	v_ashrrev_i32_e32 v3, 31, v2
	v_lshl_add_u64 v[2:3], v[2:3], 2, s[12:13]
	global_load_dword v162, v[2:3], off
	v_add_u32_e32 v2, s6, v151
	v_ashrrev_i32_e32 v3, 31, v2
	v_lshl_add_u64 v[2:3], v[2:3], 2, s[12:13]
	global_load_dword v161, v[2:3], off
	v_add_u32_e32 v2, s6, v152
	v_ashrrev_i32_e32 v3, 31, v2
	v_lshl_add_u64 v[2:3], v[2:3], 2, s[12:13]
	global_load_dword v160, v[2:3], off
	v_add_u32_e32 v2, s6, v153
	v_ashrrev_i32_e32 v3, 31, v2
	v_lshl_add_u64 v[2:3], v[2:3], 2, s[12:13]
	global_load_dword v159, v[2:3], off
	v_add_u32_e32 v2, s6, v154
	v_ashrrev_i32_e32 v3, 31, v2
	v_lshl_add_u64 v[2:3], v[2:3], 2, s[12:13]
	global_load_dword v158, v[2:3], off
	s_andn2_b64 vcc, exec, s[14:15]
	s_cbranch_vccnz .LBB0_358
	s_barrier
	s_branch .LBB0_358
